# diff-attention QK: all 4 K-fragment ds_reads issued up front (uses dead v80-87), counted lgkmcnt
# baseline (speedup 1.0000x reference)
.LBB0_311:
	ds_read_b128 v[6:9], v4 offset:12288
	ds_read_b128 v[10:13], v5 offset:12288
	ds_read_b128 v[80:83], v2 offset:12288
	ds_read_b128 v[84:87], v3 offset:12288
	s_add_i32 s8, s58, 0x7f
	s_cmp_gt_i32 s8, s54
	s_mov_b64 s[8:9], -1
	s_waitcnt lgkmcnt(3)
	v_mfma_f32_32x32x16_bf16 v[96:111], v[6:9], v[116:119], 0
	s_waitcnt lgkmcnt(2)
	v_mfma_f32_32x32x16_bf16 v[96:111], v[10:13], v[120:123], v[96:111]
	s_waitcnt lgkmcnt(1)
	v_mfma_f32_32x32x16_bf16 v[96:111], v[80:83], v[124:127], v[96:111]
	s_waitcnt lgkmcnt(0)
	v_mfma_f32_32x32x16_bf16 v[96:111], v[84:87], v[128:131], v[96:111]
	s_cbranch_scc1 .LBB0_313
	s_nop 10
	v_fmamk_f32 v80, v96, 0x3e38aa3b, v216
	v_fma_f32 v81, v97, s30, -v214
	v_fmamk_f32 v82, v98, 0x3e38aa3b, v217
	v_max3_f32 v7, v80, s52, v81
	v_fmamk_f32 v83, v99, 0x3e38aa3b, v218
	v_add_u32_e32 v6, s58, v188
	v_fmamk_f32 v84, v100, 0x3e38aa3b, v219
	v_max3_f32 v7, v7, v82, v83
	v_fmamk_f32 v85, v101, 0x3e38aa3b, v220
	v_add_u32_e32 v6, 0x60, v6
	v_fmamk_f32 v86, v102, 0x3e38aa3b, v221
	v_max3_f32 v7, v7, v84, v85
	v_fmamk_f32 v87, v103, 0x3e38aa3b, v222
	v_cvt_f32_i32_e32 v6, v6
	v_fmamk_f32 v88, v104, 0x3e38aa3b, v223
	v_max3_f32 v7, v7, v86, v87
	v_fmamk_f32 v89, v105, 0x3e38aa3b, v224
	v_fmamk_f32 v90, v106, 0x3e38aa3b, v225
	v_max3_f32 v7, v7, v88, v89
	v_fmamk_f32 v91, v107, 0x3e38aa3b, v226
	v_fmamk_f32 v92, v108, 0x3e38aa3b, v227
	v_max3_f32 v7, v7, v90, v91
	v_fmamk_f32 v93, v109, 0x3e38aa3b, v228
	v_fmamk_f32 v94, v110, 0x3e38aa3b, v229
	v_max3_f32 v7, v7, v92, v93
	v_fmamk_f32 v95, v111, 0x3e38aa3b, v230
	v_mul_f32_e64 v6, -v214, v6
	v_max3_f32 v7, v7, v94, v95
	s_mov_b64 s[8:9], 0

.LBB0_334:
	ds_read_b128 v[6:9], v4 offset:8192
	ds_read_b128 v[10:13], v5 offset:8192
	ds_read_b128 v[80:83], v2 offset:8192
	ds_read_b128 v[84:87], v3 offset:8192
	s_add_i32 s8, s58, 0x5f
	s_cmp_gt_i32 s8, s54
	s_mov_b64 s[8:9], -1
	s_waitcnt lgkmcnt(3)
	v_mfma_f32_32x32x16_bf16 v[96:111], v[6:9], v[116:119], 0
	s_waitcnt lgkmcnt(2)
	v_mfma_f32_32x32x16_bf16 v[96:111], v[10:13], v[120:123], v[96:111]
	s_waitcnt lgkmcnt(1)
	v_mfma_f32_32x32x16_bf16 v[96:111], v[80:83], v[124:127], v[96:111]
	s_waitcnt lgkmcnt(0)
	v_mfma_f32_32x32x16_bf16 v[96:111], v[84:87], v[128:131], v[96:111]
	s_cbranch_scc1 .LBB0_336
	s_nop 10
	v_fmamk_f32 v80, v96, 0x3e38aa3b, v216
	v_fma_f32 v81, v97, s30, -v214
	v_fmamk_f32 v82, v98, 0x3e38aa3b, v217
	v_max3_f32 v7, v80, s52, v81
	v_fmamk_f32 v83, v99, 0x3e38aa3b, v218
	v_fmamk_f32 v84, v100, 0x3e38aa3b, v219
	v_max3_f32 v7, v7, v82, v83
	v_fmamk_f32 v85, v101, 0x3e38aa3b, v220
	v_add3_u32 v6, v188, s58, 64
	v_fmamk_f32 v86, v102, 0x3e38aa3b, v221
	v_max3_f32 v7, v7, v84, v85
	v_fmamk_f32 v87, v103, 0x3e38aa3b, v222
	v_cvt_f32_i32_e32 v6, v6
	v_fmamk_f32 v88, v104, 0x3e38aa3b, v223
	v_max3_f32 v7, v7, v86, v87
	v_fmamk_f32 v89, v105, 0x3e38aa3b, v224
	v_fmamk_f32 v90, v106, 0x3e38aa3b, v225
	v_max3_f32 v7, v7, v88, v89
	v_fmamk_f32 v91, v107, 0x3e38aa3b, v226
	v_fmamk_f32 v92, v108, 0x3e38aa3b, v227
	v_max3_f32 v7, v7, v90, v91
	v_fmamk_f32 v93, v109, 0x3e38aa3b, v228
	v_fmamk_f32 v94, v110, 0x3e38aa3b, v229
	v_max3_f32 v7, v7, v92, v93
	v_fmamk_f32 v95, v111, 0x3e38aa3b, v230
	v_mul_f32_e64 v6, -v214, v6
	v_max3_f32 v7, v7, v94, v95
	s_mov_b64 s[8:9], 0

.LBB0_357:
	ds_read_b128 v[6:9], v4 offset:4096
	ds_read_b128 v[10:13], v5 offset:4096
	ds_read_b128 v[80:83], v2 offset:4096
	ds_read_b128 v[84:87], v3 offset:4096
	s_add_i32 s8, s58, 63
	s_cmp_gt_i32 s8, s54
	s_mov_b64 s[8:9], -1
	s_waitcnt lgkmcnt(3)
	v_mfma_f32_32x32x16_bf16 v[96:111], v[6:9], v[116:119], 0
	s_waitcnt lgkmcnt(2)
	v_mfma_f32_32x32x16_bf16 v[96:111], v[10:13], v[120:123], v[96:111]
	s_waitcnt lgkmcnt(1)
	v_mfma_f32_32x32x16_bf16 v[96:111], v[80:83], v[124:127], v[96:111]
	s_waitcnt lgkmcnt(0)
	v_mfma_f32_32x32x16_bf16 v[96:111], v[84:87], v[128:131], v[96:111]
	s_cbranch_scc1 .LBB0_359
	s_nop 10
	v_fmamk_f32 v80, v96, 0x3e38aa3b, v216
	v_fma_f32 v81, v97, s30, -v214
	v_fmamk_f32 v82, v98, 0x3e38aa3b, v217
	v_max3_f32 v7, v80, s52, v81
	v_fmamk_f32 v83, v99, 0x3e38aa3b, v218
	v_fmamk_f32 v84, v100, 0x3e38aa3b, v219
	v_max3_f32 v7, v7, v82, v83
	v_fmamk_f32 v85, v101, 0x3e38aa3b, v220
	v_add3_u32 v6, v188, s58, 32
	v_fmamk_f32 v86, v102, 0x3e38aa3b, v221
	v_max3_f32 v7, v7, v84, v85
	v_fmamk_f32 v87, v103, 0x3e38aa3b, v222
	v_cvt_f32_i32_e32 v6, v6
	v_fmamk_f32 v88, v104, 0x3e38aa3b, v223
	v_max3_f32 v7, v7, v86, v87
	v_fmamk_f32 v89, v105, 0x3e38aa3b, v224
	v_fmamk_f32 v90, v106, 0x3e38aa3b, v225
	v_max3_f32 v7, v7, v88, v89
	v_fmamk_f32 v91, v107, 0x3e38aa3b, v226
	v_fmamk_f32 v92, v108, 0x3e38aa3b, v227
	v_max3_f32 v7, v7, v90, v91
	v_fmamk_f32 v93, v109, 0x3e38aa3b, v228
	v_fmamk_f32 v94, v110, 0x3e38aa3b, v229
	v_max3_f32 v7, v7, v92, v93
	v_fmamk_f32 v95, v111, 0x3e38aa3b, v230
	v_mul_f32_e64 v6, -v214, v6
	v_max3_f32 v7, v7, v94, v95
	s_mov_b64 s[8:9], 0

.LBB0_380:
	ds_read_b128 v[6:9], v4
	ds_read_b128 v[10:13], v5
	ds_read_b128 v[80:83], v2
	ds_read_b128 v[84:87], v3
	s_add_i32 s42, s58, 31
	s_mov_b64 s[8:9], -1
	s_cmp_gt_i32 s42, s54
	v_add_u32_e32 v2, s58, v188
	s_waitcnt lgkmcnt(3)
	v_mfma_f32_32x32x16_bf16 v[96:111], v[6:9], v[116:119], 0
	s_waitcnt lgkmcnt(2)
	v_mfma_f32_32x32x16_bf16 v[96:111], v[10:13], v[120:123], v[96:111]
	s_waitcnt lgkmcnt(1)
	v_mfma_f32_32x32x16_bf16 v[96:111], v[80:83], v[124:127], v[96:111]
	s_waitcnt lgkmcnt(0)
	v_mfma_f32_32x32x16_bf16 v[96:111], v[84:87], v[128:131], v[96:111]
	s_cbranch_scc1 .LBB0_382
	s_nop 10
	v_fmamk_f32 v80, v96, 0x3e38aa3b, v216
	v_fma_f32 v81, v97, s30, -v214
	v_fmamk_f32 v82, v98, 0x3e38aa3b, v217
	v_max3_f32 v4, v80, s52, v81
	v_fmamk_f32 v83, v99, 0x3e38aa3b, v218
	v_fmamk_f32 v84, v100, 0x3e38aa3b, v219
	v_max3_f32 v4, v4, v82, v83
	v_fmamk_f32 v85, v101, 0x3e38aa3b, v220
	v_fmamk_f32 v86, v102, 0x3e38aa3b, v221
	v_max3_f32 v4, v4, v84, v85
	v_fmamk_f32 v87, v103, 0x3e38aa3b, v222
	v_cvt_f32_i32_e32 v3, v2
	v_fmamk_f32 v88, v104, 0x3e38aa3b, v223
	v_max3_f32 v4, v4, v86, v87
	v_fmamk_f32 v89, v105, 0x3e38aa3b, v224
	v_fmamk_f32 v90, v106, 0x3e38aa3b, v225
	v_max3_f32 v4, v4, v88, v89
	v_fmamk_f32 v91, v107, 0x3e38aa3b, v226
	v_fmamk_f32 v92, v108, 0x3e38aa3b, v227
	v_max3_f32 v4, v4, v90, v91
	v_fmamk_f32 v93, v109, 0x3e38aa3b, v228
	v_fmamk_f32 v94, v110, 0x3e38aa3b, v229
	v_max3_f32 v4, v4, v92, v93
	v_fmamk_f32 v95, v111, 0x3e38aa3b, v230
	v_mul_f32_e64 v3, -v214, v3
	v_max3_f32 v4, v4, v94, v95
	s_mov_b64 s[8:9], 0
